# non-temporal (nt) stores for the up-proj activation output (256MiB/layer streamed, not re-read from L2); plus SWA bias straight-line
# speedup vs baseline: 1.0082x; 1.0062x over previous
.LBB0_795:
	s_lshl_b32 s13, s43, 10
	s_add_i32 s13, s13, 0x20400
	v_lshl_or_b32 v141, v146, 2, s13
	ds_read_b32 v150, v141
	v_lshl_add_u32 v140, s45, 8, v144
	v_lshl_or_b32 v142, s44, 8, v147
	v_ashrrev_i32_e32 v141, 31, v140
	v_ashrrev_i32_e32 v143, 31, v142
	s_waitcnt lgkmcnt(0)
	v_pk_mul_f32 v[122:123], v[122:123], v[150:151] op_sel_hi:[1,0]
	v_pk_mul_f32 v[126:127], v[126:127], v[150:151] op_sel_hi:[1,0]
	v_pk_mul_f32 v[124:125], v[124:125], v[150:151] op_sel_hi:[1,0]
	v_med3_f32 v122, v122, 0, v209
	v_lshlrev_b64 v[152:153], 13, v[140:141]
	v_pk_mul_f32 v[128:129], v[128:129], v[150:151] op_sel_hi:[1,0]
	v_mul_f32_e32 v141, v122, v122
	v_med3_f32 v122, v127, 0, v209
	v_med3_f32 v123, v123, 0, v209
	v_med3_f32 v124, v124, 0, v209
	v_lshl_add_u64 v[152:153], s[8:9], 0, v[152:153]
	v_lshlrev_b64 v[142:143], 1, v[142:143]
	v_med3_f32 v126, v126, 0, v209
	v_mul_f32_e32 v122, v122, v122
	v_mul_f32_e32 v127, v123, v123
	v_med3_f32 v123, v128, 0, v209
	v_mul_f32_e32 v128, v124, v124
	v_med3_f32 v124, v129, 0, v209
	v_med3_f32 v125, v125, 0, v209
	v_pk_mul_f32 v[114:115], v[114:115], v[150:151] op_sel_hi:[1,0]
	v_lshl_add_u64 v[152:153], v[152:153], 0, v[142:143]
	v_mul_f32_e32 v126, v126, v126
	v_mul_f32_e32 v123, v123, v123
	v_mul_f32_e32 v124, v124, v124
	v_mul_f32_e32 v125, v125, v125
	v_cvt_pk_bf16_f32 v122, v126, v122
	v_pk_mul_f32 v[120:121], v[120:121], v[150:151] op_sel_hi:[1,0]
	v_pk_mul_f32 v[118:119], v[118:119], v[150:151] op_sel_hi:[1,0]
	v_pk_mul_f32 v[116:117], v[116:117], v[150:151] op_sel_hi:[1,0]
	v_med3_f32 v114, v114, 0, v209
	v_med3_f32 v115, v115, 0, v209
	v_cvt_pk_bf16_f32 v123, v123, v124
	v_cvt_pk_bf16_f32 v124, v141, v127
	v_cvt_pk_bf16_f32 v125, v128, v125
	global_store_dwordx4 v[152:153], v[122:125], off nt
	v_med3_f32 v116, v116, 0, v209
	v_med3_f32 v118, v118, 0, v209
	v_mul_f32_e32 v122, v114, v114
	v_med3_f32 v114, v119, 0, v209
	v_mul_f32_e32 v119, v115, v115
	v_med3_f32 v115, v120, 0, v209
	v_mul_f32_e32 v114, v114, v114
	v_mul_f32_e32 v115, v115, v115
	v_mul_f32_e32 v120, v116, v116
	v_med3_f32 v116, v121, 0, v209
	v_med3_f32 v117, v117, 0, v209
	v_mul_f32_e32 v118, v118, v118
	v_mul_f32_e32 v116, v116, v116
	v_mul_f32_e32 v117, v117, v117
	v_cvt_pk_bf16_f32 v114, v118, v114
	v_cvt_pk_bf16_f32 v115, v115, v116
	v_cvt_pk_bf16_f32 v116, v122, v119
	v_cvt_pk_bf16_f32 v117, v120, v117
	global_store_dwordx4 v[152:153], v[114:117], off offset:256 nt
	s_andn2_b64 vcc, exec, s[4:5]
	s_mov_b64 s[4:5], -1
	v_bitop3_b32 v115, v140, s83, 16 bitop3:0xc8
	v_lshl_or_b32 v115, v115, 2, s13
	ds_read_b32 v116, v115
	v_or_b32_e32 v114, 16, v140
	v_ashrrev_i32_e32 v115, 31, v114
	v_lshlrev_b64 v[114:115], 13, v[114:115]
	v_lshl_add_u64 v[114:115], s[8:9], 0, v[114:115]
	s_waitcnt lgkmcnt(0)
	v_pk_mul_f32 v[106:107], v[106:107], v[116:117] op_sel_hi:[1,0]
	v_pk_mul_f32 v[110:111], v[110:111], v[116:117] op_sel_hi:[1,0]
	v_pk_mul_f32 v[108:109], v[108:109], v[116:117] op_sel_hi:[1,0]
	v_med3_f32 v106, v106, 0, v209
	v_pk_mul_f32 v[112:113], v[112:113], v[116:117] op_sel_hi:[1,0]
	v_mul_f32_e32 v117, v106, v106
	v_med3_f32 v106, v111, 0, v209
	v_med3_f32 v107, v107, 0, v209
	v_med3_f32 v108, v108, 0, v209
	v_med3_f32 v110, v110, 0, v209
	v_mul_f32_e32 v106, v106, v106
	v_mul_f32_e32 v111, v107, v107
	v_med3_f32 v107, v112, 0, v209
	v_mul_f32_e32 v112, v108, v108
	v_med3_f32 v108, v113, 0, v209
	v_med3_f32 v109, v109, 0, v209
	v_pk_mul_f32 v[98:99], v[98:99], v[116:117] op_sel_hi:[1,0]
	v_lshl_add_u64 v[114:115], v[114:115], 0, v[142:143]
	v_mul_f32_e32 v110, v110, v110
	v_mul_f32_e32 v107, v107, v107
	v_mul_f32_e32 v108, v108, v108
	v_mul_f32_e32 v109, v109, v109
	v_cvt_pk_bf16_f32 v106, v110, v106
	v_pk_mul_f32 v[104:105], v[104:105], v[116:117] op_sel_hi:[1,0]
	v_pk_mul_f32 v[102:103], v[102:103], v[116:117] op_sel_hi:[1,0]
	v_pk_mul_f32 v[100:101], v[100:101], v[116:117] op_sel_hi:[1,0]
	v_med3_f32 v98, v98, 0, v209
	v_med3_f32 v99, v99, 0, v209
	v_cvt_pk_bf16_f32 v107, v107, v108
	v_cvt_pk_bf16_f32 v108, v117, v111
	v_cvt_pk_bf16_f32 v109, v112, v109
	global_store_dwordx4 v[114:115], v[106:109], off nt
	v_med3_f32 v100, v100, 0, v209
	v_med3_f32 v102, v102, 0, v209
	v_mul_f32_e32 v106, v98, v98
	v_med3_f32 v98, v103, 0, v209
	v_mul_f32_e32 v103, v99, v99
	v_med3_f32 v99, v104, 0, v209
	v_mul_f32_e32 v98, v98, v98
	v_mul_f32_e32 v99, v99, v99
	v_mul_f32_e32 v104, v100, v100
	v_med3_f32 v100, v105, 0, v209
	v_med3_f32 v101, v101, 0, v209
	v_mul_f32_e32 v102, v102, v102
	v_mul_f32_e32 v100, v100, v100
	v_mul_f32_e32 v101, v101, v101
	v_cvt_pk_bf16_f32 v98, v102, v98
	v_cvt_pk_bf16_f32 v99, v99, v100
	v_cvt_pk_bf16_f32 v100, v106, v103
	v_cvt_pk_bf16_f32 v101, v104, v101
	global_store_dwordx4 v[114:115], v[98:101], off offset:256 nt
	s_nop 1
	v_bitop3_b32 v99, v140, s95, 32 bitop3:0xc8
	v_lshl_or_b32 v99, v99, 2, s13
	ds_read_b32 v100, v99
	v_or_b32_e32 v98, 32, v140
	v_ashrrev_i32_e32 v99, 31, v98
	v_lshlrev_b64 v[98:99], 13, v[98:99]
	v_lshl_add_u64 v[98:99], s[8:9], 0, v[98:99]
	s_waitcnt lgkmcnt(0)
	v_pk_mul_f32 v[90:91], v[90:91], v[100:101] op_sel_hi:[1,0]
	v_pk_mul_f32 v[94:95], v[94:95], v[100:101] op_sel_hi:[1,0]
	v_pk_mul_f32 v[92:93], v[92:93], v[100:101] op_sel_hi:[1,0]
	v_med3_f32 v90, v90, 0, v209
	v_pk_mul_f32 v[96:97], v[96:97], v[100:101] op_sel_hi:[1,0]
	v_mul_f32_e32 v101, v90, v90
	v_med3_f32 v90, v95, 0, v209
	v_med3_f32 v91, v91, 0, v209
	v_med3_f32 v92, v92, 0, v209
	v_med3_f32 v94, v94, 0, v209
	v_mul_f32_e32 v90, v90, v90
	v_mul_f32_e32 v95, v91, v91
	v_med3_f32 v91, v96, 0, v209
	v_mul_f32_e32 v96, v92, v92
	v_med3_f32 v92, v97, 0, v209
	v_med3_f32 v93, v93, 0, v209
	v_pk_mul_f32 v[82:83], v[82:83], v[100:101] op_sel_hi:[1,0]
	v_lshl_add_u64 v[98:99], v[98:99], 0, v[142:143]
	v_mul_f32_e32 v94, v94, v94
	v_mul_f32_e32 v91, v91, v91
	v_mul_f32_e32 v92, v92, v92
	v_mul_f32_e32 v93, v93, v93
	v_cvt_pk_bf16_f32 v90, v94, v90
	v_pk_mul_f32 v[88:89], v[88:89], v[100:101] op_sel_hi:[1,0]
	v_pk_mul_f32 v[86:87], v[86:87], v[100:101] op_sel_hi:[1,0]
	v_pk_mul_f32 v[84:85], v[84:85], v[100:101] op_sel_hi:[1,0]
	v_med3_f32 v82, v82, 0, v209
	v_med3_f32 v83, v83, 0, v209
	v_cvt_pk_bf16_f32 v91, v91, v92
	v_cvt_pk_bf16_f32 v92, v101, v95
	v_cvt_pk_bf16_f32 v93, v96, v93
	global_store_dwordx4 v[98:99], v[90:93], off nt
	v_med3_f32 v84, v84, 0, v209
	v_med3_f32 v86, v86, 0, v209
	v_mul_f32_e32 v90, v82, v82
	v_med3_f32 v82, v87, 0, v209
	v_mul_f32_e32 v87, v83, v83
	v_med3_f32 v83, v88, 0, v209
	v_mul_f32_e32 v82, v82, v82
	v_mul_f32_e32 v83, v83, v83
	v_mul_f32_e32 v88, v84, v84
	v_med3_f32 v84, v89, 0, v209
	v_med3_f32 v85, v85, 0, v209
	v_mul_f32_e32 v86, v86, v86
	v_mul_f32_e32 v84, v84, v84
	v_mul_f32_e32 v85, v85, v85
	v_cvt_pk_bf16_f32 v82, v86, v82
	v_cvt_pk_bf16_f32 v83, v83, v84
	v_cvt_pk_bf16_f32 v84, v90, v87
	v_cvt_pk_bf16_f32 v85, v88, v85
	global_store_dwordx4 v[98:99], v[82:85], off offset:256 nt
	s_nop 1
	v_bitop3_b32 v83, v140, s96, 48 bitop3:0xc8
	v_lshl_or_b32 v83, v83, 2, s13
	ds_read_b32 v84, v83
	v_or_b32_e32 v82, 48, v140
	v_ashrrev_i32_e32 v83, 31, v82
	v_lshlrev_b64 v[82:83], 13, v[82:83]
	v_lshl_add_u64 v[82:83], s[8:9], 0, v[82:83]
	s_waitcnt lgkmcnt(0)
	v_pk_mul_f32 v[74:75], v[74:75], v[84:85] op_sel_hi:[1,0]
	v_pk_mul_f32 v[78:79], v[78:79], v[84:85] op_sel_hi:[1,0]
	v_pk_mul_f32 v[76:77], v[76:77], v[84:85] op_sel_hi:[1,0]
	v_med3_f32 v74, v74, 0, v209
	v_pk_mul_f32 v[80:81], v[80:81], v[84:85] op_sel_hi:[1,0]
	v_mul_f32_e32 v85, v74, v74
	v_med3_f32 v74, v79, 0, v209
	v_med3_f32 v75, v75, 0, v209
	v_med3_f32 v76, v76, 0, v209
	v_med3_f32 v78, v78, 0, v209
	v_mul_f32_e32 v74, v74, v74
	v_mul_f32_e32 v79, v75, v75
	v_med3_f32 v75, v80, 0, v209
	v_mul_f32_e32 v80, v76, v76
	v_med3_f32 v76, v81, 0, v209
	v_med3_f32 v77, v77, 0, v209
	v_pk_mul_f32 v[66:67], v[66:67], v[84:85] op_sel_hi:[1,0]
	v_lshl_add_u64 v[82:83], v[82:83], 0, v[142:143]
	v_mul_f32_e32 v78, v78, v78
	v_mul_f32_e32 v75, v75, v75
	v_mul_f32_e32 v76, v76, v76
	v_mul_f32_e32 v77, v77, v77
	v_cvt_pk_bf16_f32 v74, v78, v74
	v_pk_mul_f32 v[70:71], v[70:71], v[84:85] op_sel_hi:[1,0]
	v_pk_mul_f32 v[68:69], v[68:69], v[84:85] op_sel_hi:[1,0]
	v_med3_f32 v66, v66, 0, v209
	v_cvt_pk_bf16_f32 v75, v75, v76
	v_cvt_pk_bf16_f32 v76, v85, v79
	v_cvt_pk_bf16_f32 v77, v80, v77
	global_store_dwordx4 v[82:83], v[74:77], off nt
	v_pk_mul_f32 v[72:73], v[72:73], v[84:85] op_sel_hi:[1,0]
	v_med3_f32 v67, v67, 0, v209
	v_mul_f32_e32 v74, v66, v66
	v_med3_f32 v66, v71, 0, v209
	v_med3_f32 v68, v68, 0, v209
	v_med3_f32 v70, v70, 0, v209
	v_mul_f32_e32 v66, v66, v66
	v_mul_f32_e32 v71, v67, v67
	v_med3_f32 v67, v72, 0, v209
	v_mul_f32_e32 v72, v68, v68
	v_med3_f32 v68, v73, 0, v209
	v_med3_f32 v69, v69, 0, v209
	v_mul_f32_e32 v70, v70, v70
	v_mul_f32_e32 v67, v67, v67
	v_mul_f32_e32 v68, v68, v68
	v_mul_f32_e32 v69, v69, v69
	v_cvt_pk_bf16_f32 v66, v70, v66
	v_cvt_pk_bf16_f32 v67, v67, v68
	v_cvt_pk_bf16_f32 v68, v74, v71
	v_cvt_pk_bf16_f32 v69, v72, v69
	global_store_dwordx4 v[82:83], v[66:69], off offset:256 nt
	s_nop 1
	v_add_u32_e32 v66, 0x80, v140
	v_and_b32_e32 v67, 0xcf, v66
	v_lshl_or_b32 v67, v67, 2, s13
	ds_read_b32 v68, v67
	v_ashrrev_i32_e32 v67, 31, v66
	v_lshlrev_b64 v[66:67], 13, v[66:67]
	v_lshl_add_u64 v[66:67], s[8:9], 0, v[66:67]
	v_lshl_add_u64 v[66:67], v[66:67], 0, v[142:143]
	s_waitcnt lgkmcnt(0)
	v_pk_mul_f32 v[58:59], v[58:59], v[68:69] op_sel_hi:[1,0]
	v_pk_mul_f32 v[62:63], v[62:63], v[68:69] op_sel_hi:[1,0]
	v_pk_mul_f32 v[60:61], v[60:61], v[68:69] op_sel_hi:[1,0]
	v_med3_f32 v58, v58, 0, v209
	v_pk_mul_f32 v[64:65], v[64:65], v[68:69] op_sel_hi:[1,0]
	v_mul_f32_e32 v69, v58, v58
	v_med3_f32 v58, v63, 0, v209
	v_med3_f32 v59, v59, 0, v209
	v_med3_f32 v60, v60, 0, v209
	v_med3_f32 v62, v62, 0, v209
	v_mul_f32_e32 v58, v58, v58
	v_mul_f32_e32 v63, v59, v59
	v_med3_f32 v59, v64, 0, v209
	v_mul_f32_e32 v64, v60, v60
	v_med3_f32 v60, v65, 0, v209
	v_med3_f32 v61, v61, 0, v209
	v_pk_mul_f32 v[50:51], v[50:51], v[68:69] op_sel_hi:[1,0]
	v_mul_f32_e32 v62, v62, v62
	v_mul_f32_e32 v59, v59, v59
	v_mul_f32_e32 v60, v60, v60
	v_mul_f32_e32 v61, v61, v61
	v_cvt_pk_bf16_f32 v58, v62, v58
	v_pk_mul_f32 v[54:55], v[54:55], v[68:69] op_sel_hi:[1,0]
	v_pk_mul_f32 v[52:53], v[52:53], v[68:69] op_sel_hi:[1,0]
	v_med3_f32 v50, v50, 0, v209
	v_cvt_pk_bf16_f32 v59, v59, v60
	v_cvt_pk_bf16_f32 v60, v69, v63
	v_cvt_pk_bf16_f32 v61, v64, v61
	global_store_dwordx4 v[66:67], v[58:61], off nt
	v_pk_mul_f32 v[56:57], v[56:57], v[68:69] op_sel_hi:[1,0]
	v_med3_f32 v51, v51, 0, v209
	v_mul_f32_e32 v58, v50, v50
	v_med3_f32 v50, v55, 0, v209
	v_med3_f32 v52, v52, 0, v209
	v_med3_f32 v54, v54, 0, v209
	v_mul_f32_e32 v50, v50, v50
	v_mul_f32_e32 v55, v51, v51
	v_med3_f32 v51, v56, 0, v209
	v_mul_f32_e32 v56, v52, v52
	v_med3_f32 v52, v57, 0, v209
	v_med3_f32 v53, v53, 0, v209
	v_mul_f32_e32 v54, v54, v54
	v_mul_f32_e32 v51, v51, v51
	v_mul_f32_e32 v52, v52, v52
	v_mul_f32_e32 v53, v53, v53
	v_cvt_pk_bf16_f32 v50, v54, v50
	v_cvt_pk_bf16_f32 v51, v51, v52
	v_cvt_pk_bf16_f32 v52, v58, v55
	v_cvt_pk_bf16_f32 v53, v56, v53
	global_store_dwordx4 v[66:67], v[50:53], off offset:256 nt
	s_nop 1
	v_add_u32_e32 v50, 0x90, v140
	v_and_b32_e32 v51, 0xdf, v50
	v_lshl_or_b32 v51, v51, 2, s13
	ds_read_b32 v52, v51
	v_ashrrev_i32_e32 v51, 31, v50
	v_lshlrev_b64 v[50:51], 13, v[50:51]
	v_lshl_add_u64 v[50:51], s[8:9], 0, v[50:51]
	v_lshl_add_u64 v[50:51], v[50:51], 0, v[142:143]
	s_waitcnt lgkmcnt(0)
	v_pk_mul_f32 v[42:43], v[42:43], v[52:53] op_sel_hi:[1,0]
	v_pk_mul_f32 v[46:47], v[46:47], v[52:53] op_sel_hi:[1,0]
	v_pk_mul_f32 v[44:45], v[44:45], v[52:53] op_sel_hi:[1,0]
	v_med3_f32 v42, v42, 0, v209
	v_pk_mul_f32 v[48:49], v[48:49], v[52:53] op_sel_hi:[1,0]
	v_mul_f32_e32 v53, v42, v42
	v_med3_f32 v42, v47, 0, v209
	v_med3_f32 v43, v43, 0, v209
	v_med3_f32 v44, v44, 0, v209
	v_med3_f32 v46, v46, 0, v209
	v_mul_f32_e32 v42, v42, v42
	v_mul_f32_e32 v47, v43, v43
	v_med3_f32 v43, v48, 0, v209
	v_mul_f32_e32 v48, v44, v44
	v_med3_f32 v44, v49, 0, v209
	v_med3_f32 v45, v45, 0, v209
	v_pk_mul_f32 v[34:35], v[34:35], v[52:53] op_sel_hi:[1,0]
	v_mul_f32_e32 v46, v46, v46
	v_mul_f32_e32 v43, v43, v43
	v_mul_f32_e32 v44, v44, v44
	v_mul_f32_e32 v45, v45, v45
	v_cvt_pk_bf16_f32 v42, v46, v42
	v_pk_mul_f32 v[38:39], v[38:39], v[52:53] op_sel_hi:[1,0]
	v_pk_mul_f32 v[36:37], v[36:37], v[52:53] op_sel_hi:[1,0]
	v_med3_f32 v34, v34, 0, v209
	v_cvt_pk_bf16_f32 v43, v43, v44
	v_cvt_pk_bf16_f32 v44, v53, v47
	v_cvt_pk_bf16_f32 v45, v48, v45
	global_store_dwordx4 v[50:51], v[42:45], off nt
	v_pk_mul_f32 v[40:41], v[40:41], v[52:53] op_sel_hi:[1,0]
	v_med3_f32 v35, v35, 0, v209
	v_mul_f32_e32 v42, v34, v34
	v_med3_f32 v34, v39, 0, v209
	v_med3_f32 v36, v36, 0, v209
	v_med3_f32 v38, v38, 0, v209
	v_mul_f32_e32 v34, v34, v34
	v_mul_f32_e32 v39, v35, v35
	v_med3_f32 v35, v40, 0, v209
	v_mul_f32_e32 v40, v36, v36
	v_med3_f32 v36, v41, 0, v209
	v_med3_f32 v37, v37, 0, v209
	v_mul_f32_e32 v38, v38, v38
	v_mul_f32_e32 v35, v35, v35
	v_mul_f32_e32 v36, v36, v36
	v_mul_f32_e32 v37, v37, v37
	v_cvt_pk_bf16_f32 v34, v38, v34
	v_cvt_pk_bf16_f32 v35, v35, v36
	v_cvt_pk_bf16_f32 v36, v42, v39
	v_cvt_pk_bf16_f32 v37, v40, v37
	global_store_dwordx4 v[50:51], v[34:37], off offset:256 nt
	s_nop 1
	v_add_u32_e32 v34, 0xa0, v140
	v_and_b32_e32 v35, 0xef, v34
	v_lshl_or_b32 v35, v35, 2, s13
	ds_read_b32 v36, v35
	v_ashrrev_i32_e32 v35, 31, v34
	v_lshlrev_b64 v[34:35], 13, v[34:35]
	v_lshl_add_u64 v[34:35], s[8:9], 0, v[34:35]
	v_lshl_add_u64 v[34:35], v[34:35], 0, v[142:143]
	s_waitcnt lgkmcnt(0)
	v_pk_mul_f32 v[26:27], v[26:27], v[36:37] op_sel_hi:[1,0]
	v_pk_mul_f32 v[30:31], v[30:31], v[36:37] op_sel_hi:[1,0]
	v_pk_mul_f32 v[28:29], v[28:29], v[36:37] op_sel_hi:[1,0]
	v_med3_f32 v26, v26, 0, v209
	v_pk_mul_f32 v[32:33], v[32:33], v[36:37] op_sel_hi:[1,0]
	v_mul_f32_e32 v37, v26, v26
	v_med3_f32 v26, v31, 0, v209
	v_med3_f32 v27, v27, 0, v209
	v_med3_f32 v28, v28, 0, v209
	v_med3_f32 v30, v30, 0, v209
	v_mul_f32_e32 v26, v26, v26
	v_mul_f32_e32 v31, v27, v27
	v_med3_f32 v27, v32, 0, v209
	v_mul_f32_e32 v32, v28, v28
	v_med3_f32 v28, v33, 0, v209
	v_med3_f32 v29, v29, 0, v209
	v_pk_mul_f32 v[18:19], v[18:19], v[36:37] op_sel_hi:[1,0]
	v_mul_f32_e32 v30, v30, v30
	v_mul_f32_e32 v27, v27, v27
	v_mul_f32_e32 v28, v28, v28
	v_mul_f32_e32 v29, v29, v29
	v_cvt_pk_bf16_f32 v26, v30, v26
	v_pk_mul_f32 v[22:23], v[22:23], v[36:37] op_sel_hi:[1,0]
	v_pk_mul_f32 v[20:21], v[20:21], v[36:37] op_sel_hi:[1,0]
	v_med3_f32 v18, v18, 0, v209
	v_cvt_pk_bf16_f32 v27, v27, v28
	v_cvt_pk_bf16_f32 v28, v37, v31
	v_cvt_pk_bf16_f32 v29, v32, v29
	global_store_dwordx4 v[34:35], v[26:29], off nt
	v_pk_mul_f32 v[24:25], v[24:25], v[36:37] op_sel_hi:[1,0]
	v_med3_f32 v19, v19, 0, v209
	v_mul_f32_e32 v26, v18, v18
	v_med3_f32 v18, v23, 0, v209
	v_med3_f32 v20, v20, 0, v209
	v_med3_f32 v22, v22, 0, v209
	v_mul_f32_e32 v18, v18, v18
	v_mul_f32_e32 v23, v19, v19
	v_med3_f32 v19, v24, 0, v209
	v_mul_f32_e32 v24, v20, v20
	v_med3_f32 v20, v25, 0, v209
	v_med3_f32 v21, v21, 0, v209
	v_mul_f32_e32 v22, v22, v22
	v_mul_f32_e32 v19, v19, v19
	v_mul_f32_e32 v20, v20, v20
	v_mul_f32_e32 v21, v21, v21
	v_cvt_pk_bf16_f32 v18, v22, v18
	v_cvt_pk_bf16_f32 v19, v19, v20
	v_cvt_pk_bf16_f32 v20, v26, v23
	v_cvt_pk_bf16_f32 v21, v24, v21
	global_store_dwordx4 v[34:35], v[18:21], off offset:256 nt
	s_nop 1
	v_add_u32_e32 v18, 0xb0, v140
	v_and_b32_e32 v19, 0xff, v18
	v_lshl_or_b32 v19, v19, 2, s13
	ds_read_b32 v20, v19
	v_ashrrev_i32_e32 v19, 31, v18
	v_lshlrev_b64 v[18:19], 13, v[18:19]
	v_lshl_add_u64 v[18:19], s[8:9], 0, v[18:19]
	v_lshl_add_u64 v[18:19], v[18:19], 0, v[142:143]
	s_waitcnt lgkmcnt(0)
	v_pk_mul_f32 v[10:11], v[10:11], v[20:21] op_sel_hi:[1,0]
	v_pk_mul_f32 v[14:15], v[14:15], v[20:21] op_sel_hi:[1,0]
	v_pk_mul_f32 v[12:13], v[12:13], v[20:21] op_sel_hi:[1,0]
	v_med3_f32 v10, v10, 0, v209
	v_pk_mul_f32 v[16:17], v[16:17], v[20:21] op_sel_hi:[1,0]
	v_mul_f32_e32 v21, v10, v10
	v_med3_f32 v10, v15, 0, v209
	v_med3_f32 v11, v11, 0, v209
	v_med3_f32 v12, v12, 0, v209
	v_med3_f32 v14, v14, 0, v209
	v_mul_f32_e32 v10, v10, v10
	v_mul_f32_e32 v15, v11, v11
	v_med3_f32 v11, v16, 0, v209
	v_mul_f32_e32 v16, v12, v12
	v_med3_f32 v12, v17, 0, v209
	v_med3_f32 v13, v13, 0, v209
	v_pk_mul_f32 v[4:5], v[4:5], v[20:21] op_sel_hi:[1,0]
	v_pk_mul_f32 v[2:3], v[2:3], v[20:21] op_sel_hi:[1,0]
	v_mul_f32_e32 v14, v14, v14
	v_mul_f32_e32 v11, v11, v11
	v_mul_f32_e32 v12, v12, v12
	v_mul_f32_e32 v13, v13, v13
	v_cvt_pk_bf16_f32 v10, v14, v10
	v_pk_mul_f32 v[8:9], v[8:9], v[20:21] op_sel_hi:[1,0]
	v_pk_mul_f32 v[6:7], v[6:7], v[20:21] op_sel_hi:[1,0]
	v_med3_f32 v2, v2, 0, v209
	v_med3_f32 v3, v3, 0, v209
	v_med3_f32 v4, v4, 0, v209
	v_cvt_pk_bf16_f32 v11, v11, v12
	v_cvt_pk_bf16_f32 v12, v21, v15
	v_cvt_pk_bf16_f32 v13, v16, v13
	global_store_dwordx4 v[18:19], v[10:13], off nt
	v_med3_f32 v5, v5, 0, v209
	v_med3_f32 v6, v6, 0, v209
	v_mul_f32_e32 v10, v2, v2
	v_med3_f32 v2, v7, 0, v209
	v_mul_f32_e32 v7, v3, v3
	v_med3_f32 v3, v8, 0, v209
	v_mul_f32_e32 v8, v4, v4
	v_med3_f32 v4, v9, 0, v209
	v_mul_f32_e32 v2, v2, v2
	v_mul_f32_e32 v3, v3, v3
	v_mul_f32_e32 v4, v4, v4
	v_mul_f32_e32 v5, v5, v5
	v_mul_f32_e32 v6, v6, v6
	v_cvt_pk_bf16_f32 v2, v6, v2
	v_cvt_pk_bf16_f32 v3, v3, v4
	v_cvt_pk_bf16_f32 v4, v10, v7
	v_cvt_pk_bf16_f32 v5, v8, v5
	global_store_dwordx4 v[18:19], v[2:5], off offset:256 nt
	s_cbranch_vccnz .LBB0_784
	s_andn2_b64 vcc, exec, s[6:7]
	s_cbranch_vccnz .LBB0_783
	s_barrier
	s_branch .LBB0_783
